# GEMM: next-tile coordinate/base arithmetic made branch-free SALU and issued inside the MFMA stream of the peeled first k-iteration instead of between tiles
# baseline (speedup 1.0000x reference)
; #define PG8_STAGE(bufoff, gbase, voff) do { _Pragma("unroll") for (int _i = 0; _i < 2; ++_i) \
;         __builtin_amdgcn_global_load_lds((const unsigned*)((const char*)(gbase) + (voff)[_i]), (LAS unsigned*)(lds + (bufoff) + ldsw + _i * 8192), 16, 0, 0); } while (0)
; #define PG8_LDA(dst, b, h) do { _Pragma("unroll") for (int m = 0; m < 4; ++m) _Pragma("unroll") for (int k = 0; k < 2; ++k) dst[m][k] = *(const LAS bf16x8*)(lds + PG8_SA(b, h) + aoff + m * 2048 + k * 1024); } while (0)
; #define PG8_LDB(dst, b, h) do { _Pragma("unroll") for (int n = 0; n < 2; ++n) _Pragma("unroll") for (int k = 0; k < 2; ++k) dst[n][k] = *(const LAS bf16x8*)(lds + PG8_SB(b, h) + boff + n * 2048 + k * 1024); } while (0)
; #define PG8_BAR __builtin_amdgcn_s_barrier()
;     __host__ __device__ bool next(int i, Unit& u) const {
;         const long L = (long)i * G + c; if (L >= nwg) return false;
;         int wgid = (int)L; { const int q = nwg / NXCD, r = nwg % NXCD, xcd = wgid % NXCD, off = wgid / NXCD; wgid = (xcd < r ? xcd * (q + 1) : r * (q + 1) + (xcd - r) * q) + off; }
;         const int nig = WGM * nN, gid = wgid / nig, fm = gid * WGM, gsz = (nM - fm) < WGM ? (nM - fm) : WGM;
;         u.pm = fm + ((wgid % nig) % gsz); u.pn = (wgid % nig) / gsz; return true;
; template <class Epi>
; __device__ __forceinline__ void gemm_phase(LAS unsigned char* lds, const Gemm g, const StaticOrder& S, const Epi& E) {
;     ...
;         const bool has_next = S.next(ui + 1, nxt);
;         const char* nA = has_next ? (const char*)g.A + (size_t)nxt.pm * tstep : cA; const char* nB = has_next ? (const char*)g.Bt + (size_t)nxt.pn * tstep : cB;
;         for (int t = 0; t < nt; t += 2) {
;             const bool last = (t == nt - 2);
;             const char* a1 = cA + (size_t)(t + 1) * kstep;
;             const char* a2 = last ? nA : cA + (size_t)(t + 2) * kstep; const char* b2 = last ? nB : cB + (size_t)(t + 2) * kstep;
;             const char* a3 = a2 + kstep; const char* b3 = b2 + kstep;
;             PG8_LDB(B0, 0, 0); PG8_LDB(B1, 0, 1); PG8_SCHED; PG8_LDA(At, 0, 0); PG8_STAGE(PG8_SA(1, 1), a1 + hstep, voffA);
;             PG8_WAIT_V(8); PG8_WAIT_L(0); PG8_BAR; PG8_MMA(0, 0, At, B0); PG8_MMA(0, 1, At, B1); PG8_BAR; PG8_SCHED;
;             PG8_LDA(At, 0, 1); PG8_STAGE(PG8_SB(0, 0), b2, voffB); PG8_STAGE(PG8_SB(0, 1), b2 + hstep, voffB); PG8_STAGE(PG8_SA(0, 0), a2, voffA);
.LBB0_215:
	s_mov_b64 s[48:49], s[6:7]
	s_mov_b64 s[50:51], s[4:5]
.LBB0_221:
	s_add_u32 s0, s6, 0x80
	s_addc_u32 s1, s7, 0
	s_add_u32 s6, s4, 0x100
	s_addc_u32 s7, s5, 0
	s_mov_b32 s4, 0
	s_waitcnt vmcnt(0)
	s_add_i32 s71, s4, 2
	s_add_u32 s72, s0, 0x80
	s_addc_u32 s5, s1, 0
	s_add_i32 s74, 0, 0x10000
	s_cmp_eq_u32 s62, s4
	s_cselect_b32 s5, s49, s5
	s_cselect_b32 s4, s48, s72
	s_cselect_b32 s73, s51, s7
	s_cselect_b32 s72, s50, s6
	s_add_i32 s75, 0, 0x14000
	v_add_u32_e32 v140, s74, v245
	v_add_u32_e32 v156, s75, v245
	ds_read_b128 v[128:131], v140
	ds_read_b128 v[132:135], v140 offset:1024
	ds_read_b128 v[136:139], v140 offset:2048
	ds_read_b128 v[140:143], v140 offset:3072
	ds_read_b128 v[144:147], v156
	ds_read_b128 v[148:151], v156 offset:1024
	ds_read_b128 v[152:155], v156 offset:2048
	ds_read_b128 v[156:159], v156 offset:3072
	v_lshl_add_u64 v[212:213], s[0:1], 0, v[208:209]
	s_add_i32 m0, s55, 0xc000
	ds_read_b128 v[160:163], v247
	ds_read_b128 v[164:167], v247 offset:1024
	ds_read_b128 v[168:171], v247 offset:2048
	ds_read_b128 v[172:175], v247 offset:3072
	ds_read_b128 v[176:179], v247 offset:4096
	ds_read_b128 v[180:183], v247 offset:5120
	ds_read_b128 v[184:187], v247 offset:6144
	ds_read_b128 v[188:191], v247 offset:7168
	global_load_lds_dwordx4 v[212:213], off
	v_lshl_add_u64 v[212:213], s[0:1], 0, v[210:211]
	s_add_i32 m0, s55, 0xe000
	s_nop 0
	global_load_lds_dwordx4 v[212:213], off
	s_waitcnt vmcnt(8)
	s_waitcnt lgkmcnt(0)
	s_barrier
	s_setprio 1
	s_waitcnt lgkmcnt(0)
	v_mfma_f32_16x16x32_bf16 v[124:127], v[128:131], v[160:163], 0
	s_add_i32 s63, s63, 1
	s_mul_i32 s40, s63, s82
	v_mfma_f32_16x16x32_bf16 v[120:123], v[136:139], v[160:163], 0
	s_add_i32 s40, s40, s76
	s_cmp_lt_u32 s40, s30
	v_mfma_f32_16x16x32_bf16 v[108:111], v[128:131], v[168:171], 0
	s_cselect_b32 s32, 1, 0
	s_and_b32 vcc_lo, s40, 7
	v_mfma_f32_16x16x32_bf16 v[104:107], v[136:139], v[168:171], 0
	s_lshr_b32 vcc_hi, s40, 3
	s_mul_i32 vcc_lo, vcc_lo, s65
	v_mfma_f32_16x16x32_bf16 v[92:95], v[128:131], v[176:179], 0
	s_add_i32 s40, vcc_lo, vcc_hi
	s_mul_hi_u32 s67, s40, s66
	v_mfma_f32_16x16x32_bf16 v[88:91], v[136:139], v[176:179], 0
	s_mul_i32 s68, s67, s64
	s_sub_i32 s68, s40, s68
	v_mfma_f32_16x16x32_bf16 v[76:79], v[128:131], v[184:187], 0
	s_add_i32 vcc_lo, s67, 1
	s_sub_i32 vcc_hi, s68, s64
	v_mfma_f32_16x16x32_bf16 v[72:75], v[136:139], v[184:187], 0
	s_cmp_ge_u32 s68, s64
	s_cselect_b32 s67, vcc_lo, s67
	v_mfma_f32_16x16x32_bf16 v[124:127], v[132:135], v[164:167], v[124:127]
	s_cselect_b32 s68, vcc_hi, s68
	s_add_i32 vcc_lo, s67, 1
	v_mfma_f32_16x16x32_bf16 v[120:123], v[140:143], v[164:167], v[120:123]
	s_sub_i32 vcc_hi, s68, s64
	s_cmp_ge_u32 s68, s64
	v_mfma_f32_16x16x32_bf16 v[108:111], v[132:135], v[172:175], v[108:111]
	s_cselect_b32 s67, vcc_lo, s67
	s_cselect_b32 s68, vcc_hi, s68
	v_mfma_f32_16x16x32_bf16 v[104:107], v[140:143], v[172:175], v[104:107]
	s_lshl_b32 vcc_lo, s67, 3
	s_and_b32 vcc_hi, s68, 7
	v_mfma_f32_16x16x32_bf16 v[92:95], v[132:135], v[180:183], v[92:95]
	s_lshr_b32 s67, s68, 3
	s_add_i32 s68, vcc_hi, vcc_lo
	v_mfma_f32_16x16x32_bf16 v[88:91], v[140:143], v[180:183], v[88:91]
	s_mul_i32 vcc_lo, s34, s68
	s_mul_hi_u32 vcc_hi, s34, s68
	v_mfma_f32_16x16x32_bf16 v[76:79], v[132:135], v[188:191], v[76:79]
	s_add_u32 vcc_lo, s18, vcc_lo
	s_addc_u32 vcc_hi, s19, vcc_hi
	v_mfma_f32_16x16x32_bf16 v[72:75], v[140:143], v[188:191], v[72:75]
	s_cmp_lg_u32 s32, 0
	s_cselect_b32 s48, vcc_lo, s48
	s_setprio 0
	s_setprio 1
	v_mfma_f32_16x16x32_bf16 v[116:119], v[144:147], v[160:163], 0
	s_cselect_b32 s49, vcc_hi, s49
	s_mul_i32 vcc_lo, s34, s67
	v_mfma_f32_16x16x32_bf16 v[112:115], v[152:155], v[160:163], 0
	s_mul_hi_u32 vcc_hi, s34, s67
	s_add_u32 vcc_lo, s10, vcc_lo
	v_mfma_f32_16x16x32_bf16 v[100:103], v[144:147], v[168:171], 0
	s_addc_u32 vcc_hi, s11, vcc_hi
	s_cmp_lg_u32 s32, 0
	v_mfma_f32_16x16x32_bf16 v[96:99], v[152:155], v[168:171], 0
	s_cselect_b32 s50, vcc_lo, s50
	s_cselect_b32 s51, vcc_hi, s51
	v_mfma_f32_16x16x32_bf16 v[84:87], v[144:147], v[176:179], 0
	s_cselect_b64 s[40:41], 0, -1
	v_mfma_f32_16x16x32_bf16 v[80:83], v[152:155], v[176:179], 0
	v_mfma_f32_16x16x32_bf16 v[68:71], v[144:147], v[184:187], 0
	v_mfma_f32_16x16x32_bf16 v[64:67], v[152:155], v[184:187], 0
	v_mfma_f32_16x16x32_bf16 v[116:119], v[148:151], v[164:167], v[116:119]
	v_mfma_f32_16x16x32_bf16 v[112:115], v[156:159], v[164:167], v[112:115]
	v_mfma_f32_16x16x32_bf16 v[100:103], v[148:151], v[172:175], v[100:103]
	v_mfma_f32_16x16x32_bf16 v[96:99], v[156:159], v[172:175], v[96:99]
	v_mfma_f32_16x16x32_bf16 v[84:87], v[148:151], v[180:183], v[84:87]
	v_mfma_f32_16x16x32_bf16 v[80:83], v[156:159], v[180:183], v[80:83]
	v_mfma_f32_16x16x32_bf16 v[68:71], v[148:151], v[188:191], v[68:71]
	v_mfma_f32_16x16x32_bf16 v[64:67], v[156:159], v[188:191], v[64:67]
	s_setprio 0
	s_barrier
	s_add_i32 s74, s74, s54
	v_lshl_add_u64 v[212:213], s[72:73], 0, v[192:193]
	s_mov_b32 m0, s74
	ds_read_b128 v[160:163], v247 offset:16384
	ds_read_b128 v[164:167], v247 offset:17408
	ds_read_b128 v[168:171], v247 offset:18432
	ds_read_b128 v[172:175], v247 offset:19456
	ds_read_b128 v[176:179], v247 offset:20480
	ds_read_b128 v[180:183], v247 offset:21504
	ds_read_b128 v[184:187], v247 offset:22528
	ds_read_b128 v[188:191], v247 offset:23552
	global_load_lds_dwordx4 v[212:213], off
	s_add_i32 m0, s74, 0x2000
	v_lshl_add_u64 v[214:215], s[72:73], 0, v[204:205]
	s_add_u32 s72, s72, s2
	s_addc_u32 s73, s73, 0
	s_add_i32 s74, s75, s54
	global_load_lds_dwordx4 v[214:215], off
	v_lshl_add_u64 v[216:217], s[72:73], 0, v[192:193]
	s_mov_b32 m0, s74
	v_lshl_add_u64 v[218:219], s[72:73], 0, v[204:205]
	global_load_lds_dwordx4 v[216:217], off
	s_add_i32 m0, s74, 0x2000
	v_lshl_add_u64 v[220:221], s[4:5], 0, v[200:201]
	global_load_lds_dwordx4 v[218:219], off
	s_mov_b32 m0, s55
	v_lshl_add_u64 v[222:223], s[4:5], 0, v[202:203]
	global_load_lds_dwordx4 v[220:221], off
	s_mov_b32 m0, s56
	s_nop 0
	global_load_lds_dwordx4 v[222:223], off
	s_waitcnt vmcnt(8)
	s_waitcnt lgkmcnt(0)
	s_barrier
; #define PG8_STAGE(bufoff, gbase, voff) do { _Pragma("unroll") for (int _i = 0; _i < 2; ++_i) \
;         __builtin_amdgcn_global_load_lds((const unsigned*)((const char*)(gbase) + (voff)[_i]), (LAS unsigned*)(lds + (bufoff) + ldsw + _i * 8192), 16, 0, 0); } while (0)
; #define PG8_LDA(dst, b, h) do { _Pragma("unroll") for (int m = 0; m < 4; ++m) _Pragma("unroll") for (int k = 0; k < 2; ++k) dst[m][k] = *(const LAS bf16x8*)(lds + PG8_SA(b, h) + aoff + m * 2048 + k * 1024); } while (0)
; #define PG8_LDB(dst, b, h) do { _Pragma("unroll") for (int n = 0; n < 2; ++n) _Pragma("unroll") for (int k = 0; k < 2; ++k) dst[n][k] = *(const LAS bf16x8*)(lds + PG8_SB(b, h) + boff + n * 2048 + k * 1024); } while (0)
; #define PG8_MMA(ai, bj, At, Bt) do { __builtin_amdgcn_s_setprio(1); _Pragma("unroll") for (int m = 0; m < 4; ++m) _Pragma("unroll") for (int n = 0; n < 2; ++n) _Pragma("unroll") for (int k = 0; k < 2; ++k) \
;         acc[ai][bj][m][n] = __builtin_amdgcn_mfma_f32_16x16x32_bf16(Bt[n][k], At[m][k], acc[ai][bj][m][n], 0, 0, 0); __builtin_amdgcn_s_setprio(0); } while (0)
; #define PG8_WAIT_V(n) asm volatile("s_waitcnt vmcnt(" #n ")" ::: "memory")
; #define PG8_WAIT_L(n) asm volatile("s_waitcnt lgkmcnt(" #n ")" ::: "memory")
; #define PG8_BAR __builtin_amdgcn_s_barrier()
; #define PG8_SCHED __builtin_amdgcn_sched_barrier(0)
; template <class Epi>
; __device__ __forceinline__ void gemm_phase(LAS unsigned char* lds, const Gemm g, const StaticOrder& S, const Epi& E) {
;     ...
;             PG8_LDA(At, 0, 1); PG8_STAGE(PG8_SB(0, 0), b2, voffB); PG8_STAGE(PG8_SB(0, 1), b2 + hstep, voffB); PG8_STAGE(PG8_SA(0, 0), a2, voffA);
;             PG8_WAIT_V(8); PG8_WAIT_L(0); PG8_BAR; PG8_MMA(1, 0, At, B0); PG8_MMA(1, 1, At, B1); PG8_BAR; PG8_SCHED;
;             PG8_LDB(B0, 1, 0); PG8_LDB(B1, 1, 1); PG8_SCHED; PG8_LDA(At, 1, 0); PG8_STAGE(PG8_SA(0, 1), a2 + hstep, voffA);
;             PG8_WAIT_V(8); PG8_WAIT_L(0); PG8_BAR; PG8_MMA(0, 0, At, B0); PG8_MMA(0, 1, At, B1); PG8_BAR; PG8_SCHED;
	s_setprio 1
	s_waitcnt lgkmcnt(0)
	v_mfma_f32_16x16x32_bf16 v[60:63], v[128:131], v[160:163], 0
	v_mfma_f32_16x16x32_bf16 v[56:59], v[136:139], v[160:163], 0
	v_mfma_f32_16x16x32_bf16 v[44:47], v[128:131], v[168:171], 0
	v_mfma_f32_16x16x32_bf16 v[40:43], v[136:139], v[168:171], 0
	v_mfma_f32_16x16x32_bf16 v[28:31], v[128:131], v[176:179], 0
	v_mfma_f32_16x16x32_bf16 v[24:27], v[136:139], v[176:179], 0
	v_mfma_f32_16x16x32_bf16 v[12:15], v[128:131], v[184:187], 0
	v_mfma_f32_16x16x32_bf16 v[8:11], v[136:139], v[184:187], 0
	v_mfma_f32_16x16x32_bf16 v[60:63], v[132:135], v[164:167], v[60:63]
	v_mfma_f32_16x16x32_bf16 v[56:59], v[140:143], v[164:167], v[56:59]
	v_mfma_f32_16x16x32_bf16 v[44:47], v[132:135], v[172:175], v[44:47]
	v_mfma_f32_16x16x32_bf16 v[40:43], v[140:143], v[172:175], v[40:43]
	v_mfma_f32_16x16x32_bf16 v[28:31], v[132:135], v[180:183], v[28:31]
	v_mfma_f32_16x16x32_bf16 v[24:27], v[140:143], v[180:183], v[24:27]
	v_mfma_f32_16x16x32_bf16 v[12:15], v[132:135], v[188:191], v[12:15]
	v_mfma_f32_16x16x32_bf16 v[8:11], v[140:143], v[188:191], v[8:11]
	s_setprio 0
	s_setprio 1
	v_mfma_f32_16x16x32_bf16 v[52:55], v[144:147], v[160:163], 0
	v_mfma_f32_16x16x32_bf16 v[48:51], v[152:155], v[160:163], 0
	v_mfma_f32_16x16x32_bf16 v[36:39], v[144:147], v[168:171], 0
	v_mfma_f32_16x16x32_bf16 v[32:35], v[152:155], v[168:171], 0
	v_mfma_f32_16x16x32_bf16 v[20:23], v[144:147], v[176:179], 0
	v_mfma_f32_16x16x32_bf16 v[16:19], v[152:155], v[176:179], 0
	v_mfma_f32_16x16x32_bf16 v[4:7], v[144:147], v[184:187], 0
	v_mfma_f32_16x16x32_bf16 v[0:3], v[152:155], v[184:187], 0
	v_mfma_f32_16x16x32_bf16 v[52:55], v[148:151], v[164:167], v[52:55]
	v_mfma_f32_16x16x32_bf16 v[48:51], v[156:159], v[164:167], v[48:51]
	v_mfma_f32_16x16x32_bf16 v[36:39], v[148:151], v[172:175], v[36:39]
	v_mfma_f32_16x16x32_bf16 v[32:35], v[156:159], v[172:175], v[32:35]
	v_mfma_f32_16x16x32_bf16 v[20:23], v[148:151], v[180:183], v[20:23]
	v_mfma_f32_16x16x32_bf16 v[16:19], v[156:159], v[180:183], v[16:19]
	v_mfma_f32_16x16x32_bf16 v[4:7], v[148:151], v[188:191], v[4:7]
	v_mfma_f32_16x16x32_bf16 v[0:3], v[156:159], v[188:191], v[0:3]
	s_setprio 0
	s_barrier
	s_add_i32 s72, 0, 0x18000
	s_add_i32 s73, 0, 0x1c000
	v_add_u32_e32 v140, s72, v245
	v_add_u32_e32 v156, s73, v245
	ds_read_b128 v[128:131], v140
	ds_read_b128 v[132:135], v140 offset:1024
	ds_read_b128 v[136:139], v140 offset:2048
	ds_read_b128 v[140:143], v140 offset:3072
	ds_read_b128 v[144:147], v156
	ds_read_b128 v[148:151], v156 offset:1024
	ds_read_b128 v[152:155], v156 offset:2048
	ds_read_b128 v[156:159], v156 offset:3072
	s_add_u32 s4, s4, s2
	s_addc_u32 s5, s5, 0
	s_mov_b32 m0, s57
	v_lshl_add_u64 v[224:225], s[4:5], 0, v[200:201]
	ds_read_b128 v[160:163], v247 offset:32768
	ds_read_b128 v[164:167], v247 offset:33792
	ds_read_b128 v[168:171], v247 offset:34816
	ds_read_b128 v[172:175], v247 offset:35840
	ds_read_b128 v[176:179], v247 offset:36864
	ds_read_b128 v[180:183], v247 offset:37888
	ds_read_b128 v[184:187], v247 offset:38912
	ds_read_b128 v[188:191], v247 offset:39936
	global_load_lds_dwordx4 v[224:225], off
	v_lshl_add_u64 v[224:225], s[4:5], 0, v[202:203]
	s_mov_b32 m0, s58
	s_nop 0
	global_load_lds_dwordx4 v[224:225], off
	s_waitcnt vmcnt(8)
	s_waitcnt lgkmcnt(0)
	s_barrier
	s_setprio 1
	s_waitcnt lgkmcnt(0)
	v_mfma_f32_16x16x32_bf16 v[124:127], v[128:131], v[160:163], v[124:127]
	v_mfma_f32_16x16x32_bf16 v[120:123], v[136:139], v[160:163], v[120:123]
	v_mfma_f32_16x16x32_bf16 v[108:111], v[128:131], v[168:171], v[108:111]
	v_mfma_f32_16x16x32_bf16 v[104:107], v[136:139], v[168:171], v[104:107]
	v_mfma_f32_16x16x32_bf16 v[92:95], v[128:131], v[176:179], v[92:95]
	v_mfma_f32_16x16x32_bf16 v[88:91], v[136:139], v[176:179], v[88:91]
	v_mfma_f32_16x16x32_bf16 v[76:79], v[128:131], v[184:187], v[76:79]
	v_mfma_f32_16x16x32_bf16 v[72:75], v[136:139], v[184:187], v[72:75]
	v_mfma_f32_16x16x32_bf16 v[124:127], v[132:135], v[164:167], v[124:127]
	v_mfma_f32_16x16x32_bf16 v[120:123], v[140:143], v[164:167], v[120:123]
	v_mfma_f32_16x16x32_bf16 v[108:111], v[132:135], v[172:175], v[108:111]
	v_mfma_f32_16x16x32_bf16 v[104:107], v[140:143], v[172:175], v[104:107]
	v_mfma_f32_16x16x32_bf16 v[92:95], v[132:135], v[180:183], v[92:95]
	v_mfma_f32_16x16x32_bf16 v[88:91], v[140:143], v[180:183], v[88:91]
	v_mfma_f32_16x16x32_bf16 v[76:79], v[132:135], v[188:191], v[76:79]
	v_mfma_f32_16x16x32_bf16 v[72:75], v[140:143], v[188:191], v[72:75]
	s_setprio 0
	s_setprio 1
	v_mfma_f32_16x16x32_bf16 v[116:119], v[144:147], v[160:163], v[116:119]
	v_mfma_f32_16x16x32_bf16 v[112:115], v[152:155], v[160:163], v[112:115]
	v_mfma_f32_16x16x32_bf16 v[100:103], v[144:147], v[168:171], v[100:103]
	v_mfma_f32_16x16x32_bf16 v[96:99], v[152:155], v[168:171], v[96:99]
	v_mfma_f32_16x16x32_bf16 v[84:87], v[144:147], v[176:179], v[84:87]
	v_mfma_f32_16x16x32_bf16 v[80:83], v[152:155], v[176:179], v[80:83]
	v_mfma_f32_16x16x32_bf16 v[68:71], v[144:147], v[184:187], v[68:71]
	v_mfma_f32_16x16x32_bf16 v[64:67], v[152:155], v[184:187], v[64:67]
	v_mfma_f32_16x16x32_bf16 v[116:119], v[148:151], v[164:167], v[116:119]
	v_mfma_f32_16x16x32_bf16 v[112:115], v[156:159], v[164:167], v[112:115]
	v_mfma_f32_16x16x32_bf16 v[100:103], v[148:151], v[172:175], v[100:103]
	v_mfma_f32_16x16x32_bf16 v[96:99], v[156:159], v[172:175], v[96:99]
	v_mfma_f32_16x16x32_bf16 v[84:87], v[148:151], v[180:183], v[84:87]
	v_mfma_f32_16x16x32_bf16 v[80:83], v[156:159], v[180:183], v[80:83]
	v_mfma_f32_16x16x32_bf16 v[68:71], v[148:151], v[188:191], v[68:71]
	v_mfma_f32_16x16x32_bf16 v[64:67], v[156:159], v[188:191], v[64:67]
	s_setprio 0
	s_barrier
; #define PG8_STAGE(bufoff, gbase, voff) do { _Pragma("unroll") for (int _i = 0; _i < 2; ++_i) \
;         __builtin_amdgcn_global_load_lds((const unsigned*)((const char*)(gbase) + (voff)[_i]), (LAS unsigned*)(lds + (bufoff) + ldsw + _i * 8192), 16, 0, 0); } while (0)
; #define PG8_LDA(dst, b, h) do { _Pragma("unroll") for (int m = 0; m < 4; ++m) _Pragma("unroll") for (int k = 0; k < 2; ++k) dst[m][k] = *(const LAS bf16x8*)(lds + PG8_SA(b, h) + aoff + m * 2048 + k * 1024); } while (0)
; #define PG8_MMA(ai, bj, At, Bt) do { __builtin_amdgcn_s_setprio(1); _Pragma("unroll") for (int m = 0; m < 4; ++m) _Pragma("unroll") for (int n = 0; n < 2; ++n) _Pragma("unroll") for (int k = 0; k < 2; ++k) \
;         acc[ai][bj][m][n] = __builtin_amdgcn_mfma_f32_16x16x32_bf16(Bt[n][k], At[m][k], acc[ai][bj][m][n], 0, 0, 0); __builtin_amdgcn_s_setprio(0); } while (0)
; #define PG8_WAIT_V(n) asm volatile("s_waitcnt vmcnt(" #n ")" ::: "memory")
; #define PG8_WAIT_L(n) asm volatile("s_waitcnt lgkmcnt(" #n ")" ::: "memory")
; #define PG8_BAR __builtin_amdgcn_s_barrier()
; #define PG8_SCHED __builtin_amdgcn_sched_barrier(0)
; template <class Epi>
; __device__ __forceinline__ void gemm_phase(LAS unsigned char* lds, const Gemm g, const StaticOrder& S, const Epi& E) {
;     ...
;             PG8_LDA(At, 1, 1); PG8_STAGE(PG8_SB(1, 0), b3, voffB); PG8_STAGE(PG8_SB(1, 1), b3 + hstep, voffB); PG8_STAGE(PG8_SA(1, 0), a3, voffA);
;             PG8_WAIT_V(8); PG8_WAIT_L(0); PG8_BAR; PG8_MMA(1, 0, At, B0); PG8_MMA(1, 1, At, B1); PG8_BAR; PG8_SCHED;
;         }
	s_add_i32 s4, s72, s54
	v_lshl_add_u64 v[212:213], v[212:213], 0, s[12:13]
	s_mov_b32 m0, s4
	ds_read_b128 v[160:163], v247 offset:49152
	ds_read_b128 v[164:167], v247 offset:50176
	ds_read_b128 v[168:171], v247 offset:51200
	ds_read_b128 v[172:175], v247 offset:52224
	ds_read_b128 v[176:179], v247 offset:53248
	ds_read_b128 v[180:183], v247 offset:54272
	ds_read_b128 v[184:187], v247 offset:55296
	ds_read_b128 v[188:191], v247 offset:56320
	global_load_lds_dwordx4 v[212:213], off
	v_lshl_add_u64 v[212:213], v[214:215], 0, s[12:13]
	s_add_i32 m0, s4, 0x2000
	s_add_i32 s4, s73, s54
	global_load_lds_dwordx4 v[212:213], off
	v_lshl_add_u64 v[212:213], v[216:217], 0, s[12:13]
	s_mov_b32 m0, s4
	s_nop 0
	global_load_lds_dwordx4 v[212:213], off
	v_lshl_add_u64 v[212:213], v[218:219], 0, s[12:13]
	s_add_i32 m0, s4, 0x2000
	s_nop 0
	global_load_lds_dwordx4 v[212:213], off
	v_lshl_add_u64 v[212:213], v[220:221], 0, s[12:13]
	s_mov_b32 m0, s59
	s_nop 0
	global_load_lds_dwordx4 v[212:213], off
	v_lshl_add_u64 v[212:213], v[222:223], 0, s[12:13]
	s_mov_b32 m0, s60
	s_nop 0
	global_load_lds_dwordx4 v[212:213], off
	s_waitcnt vmcnt(8)
	s_waitcnt lgkmcnt(0)
	s_barrier
	s_setprio 1
	s_waitcnt lgkmcnt(0)
	v_mfma_f32_16x16x32_bf16 v[60:63], v[128:131], v[160:163], v[60:63]
	v_mfma_f32_16x16x32_bf16 v[56:59], v[136:139], v[160:163], v[56:59]
	v_mfma_f32_16x16x32_bf16 v[44:47], v[128:131], v[168:171], v[44:47]
	v_mfma_f32_16x16x32_bf16 v[40:43], v[136:139], v[168:171], v[40:43]
	v_mfma_f32_16x16x32_bf16 v[28:31], v[128:131], v[176:179], v[28:31]
	v_mfma_f32_16x16x32_bf16 v[24:27], v[136:139], v[176:179], v[24:27]
	v_mfma_f32_16x16x32_bf16 v[12:15], v[128:131], v[184:187], v[12:15]
	v_mfma_f32_16x16x32_bf16 v[8:11], v[136:139], v[184:187], v[8:11]
	v_mfma_f32_16x16x32_bf16 v[60:63], v[132:135], v[164:167], v[60:63]
	v_mfma_f32_16x16x32_bf16 v[56:59], v[140:143], v[164:167], v[56:59]
	v_mfma_f32_16x16x32_bf16 v[44:47], v[132:135], v[172:175], v[44:47]
	v_mfma_f32_16x16x32_bf16 v[40:43], v[140:143], v[172:175], v[40:43]
	v_mfma_f32_16x16x32_bf16 v[28:31], v[132:135], v[180:183], v[28:31]
	v_mfma_f32_16x16x32_bf16 v[24:27], v[140:143], v[180:183], v[24:27]
	v_mfma_f32_16x16x32_bf16 v[12:15], v[132:135], v[188:191], v[12:15]
	v_mfma_f32_16x16x32_bf16 v[8:11], v[140:143], v[188:191], v[8:11]
	s_setprio 0
	s_setprio 1
	v_mfma_f32_16x16x32_bf16 v[52:55], v[144:147], v[160:163], v[52:55]
	v_mfma_f32_16x16x32_bf16 v[48:51], v[152:155], v[160:163], v[48:51]
	v_mfma_f32_16x16x32_bf16 v[36:39], v[144:147], v[168:171], v[36:39]
	v_mfma_f32_16x16x32_bf16 v[32:35], v[152:155], v[168:171], v[32:35]
	v_mfma_f32_16x16x32_bf16 v[20:23], v[144:147], v[176:179], v[20:23]
	v_mfma_f32_16x16x32_bf16 v[16:19], v[152:155], v[176:179], v[16:19]
	v_mfma_f32_16x16x32_bf16 v[4:7], v[144:147], v[184:187], v[4:7]
	v_mfma_f32_16x16x32_bf16 v[0:3], v[152:155], v[184:187], v[0:3]
	v_mfma_f32_16x16x32_bf16 v[52:55], v[148:151], v[164:167], v[52:55]
	v_mfma_f32_16x16x32_bf16 v[48:51], v[156:159], v[164:167], v[48:51]
	v_mfma_f32_16x16x32_bf16 v[36:39], v[148:151], v[172:175], v[36:39]
	v_mfma_f32_16x16x32_bf16 v[32:35], v[156:159], v[172:175], v[32:35]
	v_mfma_f32_16x16x32_bf16 v[20:23], v[148:151], v[180:183], v[20:23]
	v_mfma_f32_16x16x32_bf16 v[16:19], v[156:159], v[180:183], v[16:19]
	v_mfma_f32_16x16x32_bf16 v[4:7], v[148:151], v[188:191], v[4:7]
	v_mfma_f32_16x16x32_bf16 v[0:3], v[156:159], v[188:191], v[0:3]
	s_setprio 0
	s_barrier
	s_add_u32 s0, s0, 0x100
	s_addc_u32 s1, s1, 0
	s_add_u32 s6, s6, 0x100
	s_addc_u32 s7, s7, 0
	s_cmp_ge_u32 s71, s61
	s_mov_b32 s4, s71
	s_cbranch_scc1 .Lk_done
